# all row phases: nt (streaming) cache policy on the residual/activation stores
# baseline (speedup 1.0000x reference)
.LBB0_41:
	s_add_i32 s4, s6, 1
	s_cmp_lt_i32 s4, s12
	v_add_co_u32_e32 v48, vcc, 0x2000000, v122
	s_cselect_b64 s[4:5], -1, 0
	s_nop 0
	v_addc_co_u32_e32 v49, vcc, 0, v123, vcc
	global_load_dwordx4 v[64:67], v[48:49], off
	global_load_dwordx4 v[68:71], v[48:49], off offset:1024
	global_load_dwordx4 v[72:75], v[122:123], off
	global_load_dwordx4 v[76:79], v[122:123], off offset:1024
	v_cndmask_b32_e64 v48, 0, 1, s[4:5]
	v_mov_b32_e32 v49, s59
	v_lshl_add_u64 v[48:49], v[48:49], 0, s[6:7]
	v_lshl_add_u64 v[124:125], v[48:49], 0, v[80:81]
	v_lshlrev_b64 v[52:53], 11, v[124:125]
	v_lshl_add_u64 v[128:129], v[114:115], 0, v[52:53]
	v_lshl_add_u64 v[126:127], v[116:117], 0, v[52:53]
	global_load_dwordx4 v[60:63], v[128:129], off
	global_load_dwordx4 v[48:51], v[128:129], off offset:1024
	global_load_dwordx4 v[56:59], v[126:127], off
	global_load_dwordx4 v[52:55], v[126:127], off offset:1024
	s_waitcnt vmcnt(5)
	v_and_b32_e32 v161, 0xffff0000, v74
	v_and_b32_e32 v160, 0xffff0000, v72
	v_lshlrev_b32_e32 v150, 16, v66
	v_and_b32_e32 v151, 0xffff0000, v66
	v_lshlrev_b32_e32 v152, 16, v67
	v_and_b32_e32 v153, 0xffff0000, v67
	v_lshlrev_b32_e32 v154, 16, v68
	v_and_b32_e32 v155, 0xffff0000, v68
	v_lshlrev_b32_e32 v156, 16, v69
	v_and_b32_e32 v157, 0xffff0000, v69
	v_lshlrev_b32_e32 v69, 16, v74
	v_lshlrev_b32_e32 v68, 16, v72
	v_pk_mul_f32 v[66:67], v[160:161], v[160:161]
	s_waitcnt vmcnt(4)
	v_and_b32_e32 v167, 0xffff0000, v76
	v_and_b32_e32 v166, 0xffff0000, v78
	v_lshlrev_b32_e32 v163, 16, v75
	v_lshlrev_b32_e32 v162, 16, v73
	v_and_b32_e32 v74, 0xffff0000, v73
	v_pk_fma_f32 v[66:67], v[68:69], v[68:69], v[66:67]
	v_lshlrev_b32_e32 v165, 16, v76
	v_lshlrev_b32_e32 v164, 16, v78
	v_pk_mul_f32 v[72:73], v[166:167], v[166:167]
	v_and_b32_e32 v75, 0xffff0000, v75
	v_pk_fma_f32 v[66:67], v[162:163], v[162:163], v[66:67]
	v_lshlrev_b32_e32 v169, 16, v77
	v_lshlrev_b32_e32 v168, 16, v79
	v_pk_fma_f32 v[72:73], v[164:165], v[164:165], v[72:73]
	v_pk_fma_f32 v[66:67], v[74:75], v[74:75], v[66:67]
	v_and_b32_e32 v77, 0xffff0000, v77
	v_and_b32_e32 v76, 0xffff0000, v79
	v_pk_fma_f32 v[72:73], v[168:169], v[168:169], v[72:73]
	v_add_f32_e32 v66, v66, v67
	v_pk_fma_f32 v[72:73], v[76:77], v[76:77], v[72:73]
	v_lshlrev_b32_e32 v158, 16, v70
	v_add_f32_e32 v66, v66, v73
	v_add_f32_e32 v66, v72, v66
	v_and_b32_e32 v159, 0xffff0000, v70
	v_lshlrev_b32_e32 v78, 16, v71
	v_add_f32_dpp v66, v66, v66 quad_perm:[1,0,3,2] row_mask:0xf bank_mask:0xf bound_ctrl:1
	v_and_b32_e32 v79, 0xffff0000, v71
	v_mov_b32_e32 v70, v68
	v_add_f32_dpp v66, v66, v66 quad_perm:[2,3,0,1] row_mask:0xf bank_mask:0xf bound_ctrl:1
	v_mov_b32_e32 v71, v160
	v_lshlrev_b32_e32 v130, 16, v64
	v_add_f32_dpp v66, v66, v66 row_half_mirror row_mask:0xf bank_mask:0xf bound_ctrl:1
	v_and_b32_e32 v131, 0xffff0000, v64
	v_lshlrev_b32_e32 v64, 16, v65
	v_add_f32_dpp v66, v66, v66 row_mirror row_mask:0xf bank_mask:0xf bound_ctrl:1
	v_and_b32_e32 v65, 0xffff0000, v65
	v_readlane_b32 s8, v66, 16
	v_readlane_b32 s9, v66, 48
	v_readlane_b32 s4, v66, 0
	v_readlane_b32 s5, v66, 32
	v_mov_b32_e32 v66, s8
	v_mov_b32_e32 v67, s9
	v_pk_add_f32 v[66:67], s[4:5], v[66:67]
	v_mov_b32_e32 v72, v169
	v_add_f32_e32 v66, v66, v67
	v_fmamk_f32 v66, v66, 0x3a800000, v137
	v_mul_f32_e32 v67, 0x4b800000, v66
	v_cmp_gt_f32_e32 vcc, s94, v66
	v_mov_b32_e32 v73, v77
	v_mov_b32_e32 v169, v76
	v_cndmask_b32_e32 v66, v66, v67, vcc
	v_rsq_f32_e32 v66, v66
	v_mov_b32_e32 v160, v69
	s_mov_b64 s[8:9], -1
	v_mul_f32_e32 v67, 0x45800000, v66
	v_cndmask_b32_e32 v132, v66, v67, vcc
	v_mov_b32_e32 v66, v162
	v_mov_b32_e32 v67, v74
	v_pk_mul_f32 v[66:67], v[132:133], v[66:67] op_sel_hi:[0,1]
	v_pk_mul_f32 v[70:71], v[132:133], v[70:71] op_sel_hi:[0,1]
	v_pk_mul_f32 v[70:71], v[4:5], v[70:71]
	v_pk_mul_f32 v[66:67], v[6:7], v[66:67]
	v_mov_b32_e32 v74, v163
	v_pk_fma_f32 v[66:67], v[98:99], v[66:67], v[64:65]
	v_pk_fma_f32 v[64:65], v[100:101], v[70:71], v[130:131]
	v_pk_mul_f32 v[70:71], v[132:133], v[74:75] op_sel_hi:[0,1]
	v_mov_b32_e32 v74, v165
	v_mov_b32_e32 v75, v167
	v_pk_mul_f32 v[72:73], v[132:133], v[72:73] op_sel_hi:[0,1]
	v_pk_mul_f32 v[74:75], v[132:133], v[74:75] op_sel_hi:[0,1]
	v_pk_mul_f32 v[130:131], v[12:13], v[74:75]
	v_pk_mul_f32 v[72:73], v[14:15], v[72:73]
	v_mov_b32_e32 v165, v166
	v_pk_fma_f32 v[74:75], v[106:107], v[72:73], v[156:157]
	v_pk_fma_f32 v[72:73], v[108:109], v[130:131], v[154:155]
	v_pk_mul_f32 v[76:77], v[132:133], v[168:169] op_sel_hi:[0,1]
	v_pk_mul_f32 v[130:131], v[132:133], v[164:165] op_sel_hi:[0,1]
	v_pk_mul_f32 v[68:69], v[132:133], v[160:161] op_sel_hi:[0,1]
	v_pk_mul_f32 v[130:131], v[8:9], v[130:131]
	v_pk_mul_f32 v[76:77], v[10:11], v[76:77]
	v_pk_mul_f32 v[68:69], v[0:1], v[68:69]
	v_pk_mul_f32 v[70:71], v[2:3], v[70:71]
	v_pk_fma_f32 v[78:79], v[110:111], v[76:77], v[78:79]
	v_pk_fma_f32 v[76:77], v[112:113], v[130:131], v[158:159]
	v_cndmask_b32_e64 v130, 0, 1, s[2:3]
	v_pk_fma_f32 v[70:71], v[102:103], v[70:71], v[152:153]
	v_pk_fma_f32 v[68:69], v[104:105], v[68:69], v[150:151]
	v_cmp_ne_u32_e64 s[4:5], 1, v130
	s_andn2_b64 vcc, exec, s[2:3]
	s_cbranch_vccnz .LBB0_43
	s_mov_b64 s[8:9], 0x2000000
	v_lshl_add_u64 v[130:131], v[122:123], 0, s[8:9]
	v_cvt_pk_bf16_f32 v152, v68, v69
	v_cvt_pk_bf16_f32 v153, v70, v71
	v_cvt_pk_bf16_f32 v150, v64, v65
	v_cvt_pk_bf16_f32 v151, v66, v67
	global_store_dwordx4 v[130:131], v[150:153], off nt
	v_mov_b32_e32 v130, v64
	v_mov_b32_e32 v131, v68
	v_mov_b32_e32 v152, v65
	v_mov_b32_e32 v153, v69
	v_pk_mul_f32 v[152:153], v[152:153], v[152:153]
	v_mov_b32_e32 v156, v77
	v_pk_fma_f32 v[130:131], v[130:131], v[130:131], v[152:153]
	v_mov_b32_e32 v152, v66
	v_mov_b32_e32 v153, v70
	v_pk_fma_f32 v[130:131], v[152:153], v[152:153], v[130:131]
	v_mov_b32_e32 v152, v67
	v_mov_b32_e32 v153, v71
	v_mov_b32_e32 v157, v73
	v_pk_fma_f32 v[130:131], v[152:153], v[152:153], v[130:131]
	v_mov_b32_e32 v152, v76
	v_mov_b32_e32 v153, v72
	v_pk_mul_f32 v[156:157], v[156:157], v[156:157]
	v_add_f32_e32 v130, v130, v131
	v_pk_fma_f32 v[152:153], v[152:153], v[152:153], v[156:157]
	v_mov_b32_e32 v156, v78
	v_mov_b32_e32 v157, v74
	v_pk_fma_f32 v[152:153], v[156:157], v[156:157], v[152:153]
	v_mov_b32_e32 v156, v79
	v_mov_b32_e32 v157, v75
	v_pk_fma_f32 v[152:153], v[156:157], v[156:157], v[152:153]
	s_mov_b64 s[8:9], 0x2000400
	v_add_f32_e32 v130, v153, v130
	v_add_f32_e32 v130, v152, v130
	v_lshl_add_u64 v[154:155], v[122:123], 0, s[8:9]
	v_cvt_pk_bf16_f32 v150, v72, v73
	v_cvt_pk_bf16_f32 v151, v74, v75
	v_cvt_pk_bf16_f32 v152, v76, v77
	v_cvt_pk_bf16_f32 v153, v78, v79
	s_nop 0
	v_add_f32_dpp v130, v130, v130 quad_perm:[1,0,3,2] row_mask:0xf bank_mask:0xf bound_ctrl:1
	global_store_dwordx4 v[154:155], v[150:153], off nt
	s_nop 0
	v_add_f32_dpp v130, v130, v130 quad_perm:[2,3,0,1] row_mask:0xf bank_mask:0xf bound_ctrl:1
	s_nop 1
	v_add_f32_dpp v130, v130, v130 row_half_mirror row_mask:0xf bank_mask:0xf bound_ctrl:1
	s_nop 1
	v_add_f32_dpp v130, v130, v130 row_mirror row_mask:0xf bank_mask:0xf bound_ctrl:1
	s_nop 0
	v_readlane_b32 s10, v130, 16
	v_readlane_b32 s11, v130, 48
	v_readlane_b32 s8, v130, 0
	v_readlane_b32 s9, v130, 32
	v_mov_b32_e32 v130, s10
	v_mov_b32_e32 v131, s11
	v_pk_add_f32 v[130:131], s[8:9], v[130:131]
	s_mov_b64 s[8:9], 0
	v_add_f32_e32 v130, v130, v131
	v_fmamk_f32 v130, v130, 0x3a800000, v137
	v_mul_f32_e32 v131, 0x4b800000, v130
	v_cmp_gt_f32_e32 vcc, s94, v130
	s_nop 1
	v_cndmask_b32_e32 v130, v130, v131, vcc
	v_rsq_f32_e32 v130, v130
	s_nop 0
	v_mul_f32_e32 v131, 0x45800000, v130
	v_cndmask_b32_e32 v130, v130, v131, vcc
	v_pk_mul_f32 v[150:151], v[66:67], v[130:131] op_sel_hi:[1,0]
	v_pk_mul_f32 v[152:153], v[64:65], v[130:131] op_sel_hi:[1,0]
	v_pk_mul_f32 v[150:151], v[38:39], v[150:151]
	v_pk_mul_f32 v[152:153], v[36:37], v[152:153]
	v_pk_fma_f32 v[154:155], v[90:91], v[150:151], v[22:23]
	v_pk_fma_f32 v[150:151], v[88:89], v[152:153], v[20:21]
	v_pk_mul_f32 v[152:153], v[70:71], v[130:131] op_sel_hi:[1,0]
	v_pk_mul_f32 v[156:157], v[68:69], v[130:131] op_sel_hi:[1,0]
	v_pk_mul_f32 v[152:153], v[34:35], v[152:153]
	v_pk_mul_f32 v[156:157], v[32:33], v[156:157]
	v_pk_fma_f32 v[158:159], v[92:93], v[152:153], v[18:19]
	v_pk_fma_f32 v[152:153], v[84:85], v[156:157], v[16:17]
	v_pk_mul_f32 v[156:157], v[74:75], v[130:131] op_sel_hi:[1,0]
	v_pk_mul_f32 v[160:161], v[72:73], v[130:131] op_sel_hi:[1,0]
	v_pk_mul_f32 v[162:163], v[78:79], v[130:131] op_sel_hi:[1,0]
	v_pk_mul_f32 v[130:131], v[76:77], v[130:131] op_sel_hi:[1,0]
	v_pk_mul_f32 v[160:161], v[44:45], v[160:161]
	v_pk_mul_f32 v[156:157], v[46:47], v[156:157]
	v_pk_mul_f32 v[130:131], v[40:41], v[130:131]
	v_pk_mul_f32 v[162:163], v[42:43], v[162:163]
	v_cvt_pk_bf16_f32 v150, v150, v151
	v_cvt_pk_bf16_f32 v151, v154, v155
	v_cvt_pk_bf16_f32 v152, v152, v153
	v_cvt_pk_bf16_f32 v153, v158, v159
	v_pk_fma_f32 v[156:157], v[94:95], v[156:157], v[30:31]
	v_pk_fma_f32 v[160:161], v[82:83], v[160:161], v[28:29]
	v_pk_fma_f32 v[162:163], v[96:97], v[162:163], v[26:27]
	v_pk_fma_f32 v[130:131], v[86:87], v[130:131], v[24:25]
	global_store_dwordx4 v[122:123], v[150:153], off nt
	s_nop 1
	v_cvt_pk_bf16_f32 v150, v160, v161
	v_cvt_pk_bf16_f32 v151, v156, v157
	v_cvt_pk_bf16_f32 v152, v130, v131
	v_cvt_pk_bf16_f32 v153, v162, v163
	global_store_dwordx4 v[122:123], v[150:153], off offset:1024 nt
.LBB0_43:
	s_andn2_b64 vcc, exec, s[8:9]
	s_cbranch_vccnz .LBB0_45
	global_store_dwordx4 v[120:121], v[64:67], off nt
	global_store_dwordx4 v[120:121], v[68:71], off offset:16 nt
	global_store_dwordx4 v[120:121], v[72:75], off offset:2048 nt
	global_store_dwordx4 v[120:121], v[76:79], off offset:2064 nt
.LBB0_45:
	s_waitcnt vmcnt(1)
	v_and_b32_e32 v71, 0xffff0000, v58
	v_and_b32_e32 v70, 0xffff0000, v56
	v_lshlrev_b32_e32 v69, 16, v58
	v_lshlrev_b32_e32 v68, 16, v56
	v_lshlrev_b32_e32 v72, 16, v57
	v_and_b32_e32 v58, 0xffff0000, v57
	v_lshlrev_b32_e32 v56, 16, v48
	v_and_b32_e32 v57, 0xffff0000, v48
	v_lshlrev_b32_e32 v74, 16, v49
	v_and_b32_e32 v75, 0xffff0000, v49
	s_waitcnt vmcnt(0)
	v_and_b32_e32 v131, 0xffff0000, v52
	v_and_b32_e32 v130, 0xffff0000, v54
	v_pk_mul_f32 v[48:49], v[70:71], v[70:71]
	v_lshlrev_b32_e32 v73, 16, v59
	v_lshlrev_b32_e32 v79, 16, v52
	v_lshlrev_b32_e32 v78, 16, v54
	v_lshlrev_b32_e32 v151, 16, v53
	v_and_b32_e32 v153, 0xffff0000, v53
	v_pk_fma_f32 v[48:49], v[68:69], v[68:69], v[48:49]
	v_pk_mul_f32 v[52:53], v[130:131], v[130:131]
	v_and_b32_e32 v59, 0xffff0000, v59
	v_lshlrev_b32_e32 v150, 16, v55
	v_pk_fma_f32 v[48:49], v[72:73], v[72:73], v[48:49]
	v_pk_fma_f32 v[52:53], v[78:79], v[78:79], v[52:53]
	v_and_b32_e32 v152, 0xffff0000, v55
	v_pk_fma_f32 v[48:49], v[58:59], v[58:59], v[48:49]
	v_pk_fma_f32 v[52:53], v[150:151], v[150:151], v[52:53]
	v_add_f32_e32 v48, v48, v49
	v_pk_fma_f32 v[52:53], v[152:153], v[152:153], v[52:53]
	v_lshlrev_b32_e32 v76, 16, v50
	v_add_f32_e32 v48, v48, v53
	v_add_f32_e32 v48, v52, v48
	v_and_b32_e32 v77, 0xffff0000, v50
	v_lshlrev_b32_e32 v154, 16, v51
	v_add_f32_dpp v48, v48, v48 quad_perm:[1,0,3,2] row_mask:0xf bank_mask:0xf bound_ctrl:1
	v_and_b32_e32 v155, 0xffff0000, v51
	v_mov_b32_e32 v50, v68
	v_add_f32_dpp v48, v48, v48 quad_perm:[2,3,0,1] row_mask:0xf bank_mask:0xf bound_ctrl:1
	v_mov_b32_e32 v51, v70
	v_lshlrev_b32_e32 v64, 16, v60
	v_add_f32_dpp v48, v48, v48 row_half_mirror row_mask:0xf bank_mask:0xf bound_ctrl:1
	v_and_b32_e32 v65, 0xffff0000, v60
	v_lshlrev_b32_e32 v60, 16, v61
	v_add_f32_dpp v48, v48, v48 row_mirror row_mask:0xf bank_mask:0xf bound_ctrl:1
	v_and_b32_e32 v61, 0xffff0000, v61
	v_readlane_b32 s10, v48, 16
	v_readlane_b32 s11, v48, 48
	v_readlane_b32 s8, v48, 0
	v_readlane_b32 s9, v48, 32
	v_mov_b32_e32 v48, s10
	v_mov_b32_e32 v49, s11
	v_pk_add_f32 v[48:49], s[8:9], v[48:49]
	v_mov_b32_e32 v70, v69
	v_add_f32_e32 v48, v48, v49
	v_fmamk_f32 v48, v48, 0x3a800000, v137
	v_mul_f32_e32 v49, 0x4b800000, v48
	v_cmp_gt_f32_e32 vcc, s94, v48
	v_lshlrev_b32_e32 v66, 16, v62
	v_and_b32_e32 v67, 0xffff0000, v62
	v_cndmask_b32_e32 v48, v48, v49, vcc
	v_rsq_f32_e32 v48, v48
	v_lshlrev_b32_e32 v62, 16, v63
	v_and_b32_e32 v63, 0xffff0000, v63
	v_mul_f32_e32 v49, 0x45800000, v48
	v_cndmask_b32_e32 v132, v48, v49, vcc
	v_mov_b32_e32 v48, v72
	v_mov_b32_e32 v49, v58
	v_pk_mul_f32 v[48:49], v[132:133], v[48:49] op_sel_hi:[0,1]
	v_pk_mul_f32 v[50:51], v[132:133], v[50:51] op_sel_hi:[0,1]
	v_pk_mul_f32 v[52:53], v[4:5], v[50:51]
	v_pk_mul_f32 v[48:49], v[6:7], v[48:49]
	v_mov_b32_e32 v58, v73
	v_pk_fma_f32 v[50:51], v[98:99], v[48:49], v[60:61]
	v_pk_fma_f32 v[48:49], v[100:101], v[52:53], v[64:65]
	v_pk_mul_f32 v[52:53], v[132:133], v[58:59] op_sel_hi:[0,1]
	v_pk_mul_f32 v[54:55], v[132:133], v[70:71] op_sel_hi:[0,1]
	v_mov_b32_e32 v60, v79
	v_mov_b32_e32 v61, v131
	v_pk_mul_f32 v[58:59], v[0:1], v[54:55]
	v_pk_mul_f32 v[52:53], v[2:3], v[52:53]
	v_pk_mul_f32 v[60:61], v[132:133], v[60:61] op_sel_hi:[0,1]
	v_pk_fma_f32 v[54:55], v[102:103], v[52:53], v[62:63]
	v_pk_fma_f32 v[52:53], v[104:105], v[58:59], v[66:67]
	v_mov_b32_e32 v58, v151
	v_mov_b32_e32 v59, v153
	v_pk_mul_f32 v[60:61], v[12:13], v[60:61]
	v_mov_b32_e32 v151, v152
	v_mov_b32_e32 v79, v130
	v_pk_mul_f32 v[58:59], v[132:133], v[58:59] op_sel_hi:[0,1]
	v_pk_fma_f32 v[56:57], v[108:109], v[60:61], v[56:57]
	v_pk_mul_f32 v[60:61], v[132:133], v[150:151] op_sel_hi:[0,1]
	v_pk_mul_f32 v[62:63], v[132:133], v[78:79] op_sel_hi:[0,1]
	v_pk_mul_f32 v[58:59], v[14:15], v[58:59]
	v_pk_mul_f32 v[64:65], v[8:9], v[62:63]
	v_pk_mul_f32 v[60:61], v[10:11], v[60:61]
	v_pk_fma_f32 v[58:59], v[106:107], v[58:59], v[74:75]
	v_pk_fma_f32 v[62:63], v[110:111], v[60:61], v[154:155]
	v_pk_fma_f32 v[60:61], v[112:113], v[64:65], v[76:77]
	s_and_b64 vcc, exec, s[4:5]
	s_mov_b64 s[4:5], -1
	s_cbranch_vccnz .LBB0_47
	v_cvt_pk_bf16_f32 v66, v52, v53
	v_cvt_pk_bf16_f32 v67, v54, v55
	v_mov_b32_e32 v68, v49
	v_mov_b32_e32 v69, v53
	v_cvt_pk_bf16_f32 v64, v48, v49
	v_cvt_pk_bf16_f32 v65, v50, v51
	global_store_dwordx4 v[128:129], v[64:67], off nt
	v_pk_mul_f32 v[68:69], v[68:69], v[68:69]
	v_mov_b32_e32 v70, v61
	v_mov_b32_e32 v66, v48
	v_mov_b32_e32 v67, v52
	v_pk_fma_f32 v[66:67], v[66:67], v[66:67], v[68:69]
	v_mov_b32_e32 v68, v50
	v_mov_b32_e32 v69, v54
	v_pk_fma_f32 v[66:67], v[68:69], v[68:69], v[66:67]
	v_mov_b32_e32 v68, v51
	v_mov_b32_e32 v69, v55
	v_mov_b32_e32 v71, v57
	v_pk_fma_f32 v[66:67], v[68:69], v[68:69], v[66:67]
	v_mov_b32_e32 v68, v60
	v_mov_b32_e32 v69, v56
	v_pk_mul_f32 v[70:71], v[70:71], v[70:71]
	v_add_f32_e32 v66, v66, v67
	v_pk_fma_f32 v[68:69], v[68:69], v[68:69], v[70:71]
	v_mov_b32_e32 v70, v62
	v_mov_b32_e32 v71, v58
	v_pk_fma_f32 v[68:69], v[70:71], v[70:71], v[68:69]
	v_mov_b32_e32 v70, v63
	v_mov_b32_e32 v71, v59
	v_pk_fma_f32 v[68:69], v[70:71], v[70:71], v[68:69]
	v_cvt_pk_bf16_f32 v64, v56, v57
	v_cvt_pk_bf16_f32 v65, v58, v59
	s_nop 0
	v_add_f32_e32 v66, v69, v66
	v_add_f32_e32 v66, v68, v66
	s_nop 1
	v_add_f32_dpp v66, v66, v66 quad_perm:[1,0,3,2] row_mask:0xf bank_mask:0xf bound_ctrl:1
	s_nop 1
	v_add_f32_dpp v66, v66, v66 quad_perm:[2,3,0,1] row_mask:0xf bank_mask:0xf bound_ctrl:1
	s_nop 1
	v_add_f32_dpp v66, v66, v66 row_half_mirror row_mask:0xf bank_mask:0xf bound_ctrl:1
	s_nop 1
	v_add_f32_dpp v66, v66, v66 row_mirror row_mask:0xf bank_mask:0xf bound_ctrl:1
	s_nop 0
	v_readlane_b32 s8, v66, 16
	v_readlane_b32 s9, v66, 48
	v_readlane_b32 s4, v66, 0
	v_readlane_b32 s5, v66, 32
	v_mov_b32_e32 v66, s8
	v_mov_b32_e32 v67, s9
	v_pk_add_f32 v[66:67], s[4:5], v[66:67]
	s_mov_b64 s[4:5], 0
	v_add_f32_e32 v66, v66, v67
	v_fmamk_f32 v66, v66, 0x3a800000, v137
	v_mul_f32_e32 v67, 0x4b800000, v66
	v_cmp_gt_f32_e32 vcc, s94, v66
	s_nop 1
	v_cndmask_b32_e32 v66, v66, v67, vcc
	v_rsq_f32_e32 v68, v66
	v_cvt_pk_bf16_f32 v66, v60, v61
	v_cvt_pk_bf16_f32 v67, v62, v63
	global_store_dwordx4 v[128:129], v[64:67], off offset:1024 nt
	s_nop 1
	v_mul_f32_e32 v64, 0x45800000, v68
	v_cndmask_b32_e32 v64, v68, v64, vcc
	v_pk_mul_f32 v[66:67], v[50:51], v[64:65] op_sel_hi:[1,0]
	v_pk_mul_f32 v[68:69], v[48:49], v[64:65] op_sel_hi:[1,0]
	v_pk_mul_f32 v[66:67], v[38:39], v[66:67]
	v_pk_mul_f32 v[70:71], v[54:55], v[64:65] op_sel_hi:[1,0]
	v_pk_mul_f32 v[72:73], v[52:53], v[64:65] op_sel_hi:[1,0]
	v_pk_mul_f32 v[74:75], v[58:59], v[64:65] op_sel_hi:[1,0]
	v_pk_mul_f32 v[76:77], v[56:57], v[64:65] op_sel_hi:[1,0]
	v_pk_mul_f32 v[78:79], v[62:63], v[64:65] op_sel_hi:[1,0]
	v_pk_mul_f32 v[64:65], v[60:61], v[64:65] op_sel_hi:[1,0]
	v_pk_mul_f32 v[68:69], v[36:37], v[68:69]
	v_pk_fma_f32 v[66:67], v[90:91], v[66:67], v[22:23]
	v_pk_mul_f32 v[72:73], v[32:33], v[72:73]
	v_pk_mul_f32 v[70:71], v[34:35], v[70:71]
	v_pk_mul_f32 v[64:65], v[40:41], v[64:65]
	v_pk_fma_f32 v[68:69], v[88:89], v[68:69], v[20:21]
	v_pk_fma_f32 v[70:71], v[92:93], v[70:71], v[18:19]
	v_pk_fma_f32 v[72:73], v[84:85], v[72:73], v[16:17]
	v_pk_mul_f32 v[76:77], v[44:45], v[76:77]
	v_pk_mul_f32 v[74:75], v[46:47], v[74:75]
	v_pk_mul_f32 v[78:79], v[42:43], v[78:79]
	v_pk_fma_f32 v[128:129], v[86:87], v[64:65], v[24:25]
	v_cvt_pk_bf16_f32 v64, v68, v69
	v_cvt_pk_bf16_f32 v65, v66, v67
	v_cvt_pk_bf16_f32 v66, v72, v73
	v_cvt_pk_bf16_f32 v67, v70, v71
	v_pk_fma_f32 v[74:75], v[94:95], v[74:75], v[30:31]
	v_pk_fma_f32 v[76:77], v[82:83], v[76:77], v[28:29]
	v_pk_fma_f32 v[78:79], v[96:97], v[78:79], v[26:27]
	global_store_dwordx4 v[126:127], v[64:67], off nt
	s_nop 1
	v_cvt_pk_bf16_f32 v64, v76, v77
	v_cvt_pk_bf16_f32 v65, v74, v75
	v_cvt_pk_bf16_f32 v66, v128, v129
	v_cvt_pk_bf16_f32 v67, v78, v79
	global_store_dwordx4 v[126:127], v[64:67], off offset:1024 nt
.LBB0_47:
	s_andn2_b64 vcc, exec, s[4:5]
	s_cbranch_vccnz .LBB0_40
	v_lshlrev_b64 v[64:65], 12, v[124:125]
	v_lshl_add_u64 v[64:65], v[118:119], 0, v[64:65]
	global_store_dwordx4 v[64:65], v[48:51], off nt
	global_store_dwordx4 v[64:65], v[52:55], off offset:16 nt
	global_store_dwordx4 v[64:65], v[56:59], off offset:2048 nt
	global_store_dwordx4 v[64:65], v[60:63], off offset:2064 nt
	s_branch .LBB0_40

.LBB0_1254:
	s_add_i32 s4, s8, 1
	s_cmp_lt_i32 s4, s10
	s_cselect_b64 vcc, -1, 0
	v_add_u32_e32 v52, s8, v72
	v_cndmask_b32_e64 v48, 0, 1, vcc
	v_mov_b32_e32 v49, s59
	v_mov_b32_e32 v32, s8
	v_lshl_add_u64 v[50:51], v[72:73], 0, s[8:9]
	v_addc_co_u32_e64 v53, s[4:5], v72, v32, vcc
	v_lshl_add_u64 v[64:65], v[50:51], 0, v[48:49]
	v_addc_co_u32_e32 v48, vcc, v52, v214, vcc
	v_add_u32_e32 v32, 0xffffe000, v52
	v_cmp_gt_i32_e64 s[4:5], s27, v52
	v_cmp_gt_i32_e32 vcc, s27, v53
	s_waitcnt lgkmcnt(0)
	v_mov_b32_e32 v54, s7
	v_cndmask_b32_e64 v33, 0, v51, s[4:5]
	v_cndmask_b32_e64 v32, v32, v50, s[4:5]
	v_mov_b32_e32 v55, s3
	v_mov_b32_e32 v56, s6
	v_mov_b32_e32 v57, s2
	v_cndmask_b32_e32 v49, 0, v65, vcc
	v_cndmask_b32_e32 v48, v48, v64, vcc
	v_cndmask_b32_e64 v35, v54, v55, s[4:5]
	v_cndmask_b32_e64 v34, v56, v57, s[4:5]
	v_lshlrev_b64 v[32:33], 12, v[32:33]
	v_cndmask_b32_e32 v51, v54, v55, vcc
	v_cndmask_b32_e32 v50, v56, v57, vcc
	v_lshlrev_b64 v[48:49], 12, v[48:49]
	v_lshl_add_u64 v[32:33], v[34:35], 0, v[32:33]
	v_lshl_add_u64 v[48:49], v[50:51], 0, v[48:49]
	v_lshl_add_u64 v[44:45], v[32:33], 0, v[132:133]
	v_lshl_add_u64 v[60:61], v[48:49], 0, v[132:133]
	global_load_dwordx4 v[32:35], v[44:45], off offset:16
	global_load_dwordx4 v[40:43], v[44:45], off
	global_load_dwordx4 v[36:39], v[44:45], off offset:2064
	s_nop 0
	global_load_dwordx4 v[44:47], v[44:45], off offset:2048
	s_nop 0
	global_load_dwordx4 v[48:51], v[60:61], off offset:16
	global_load_dwordx4 v[56:59], v[60:61], off
	global_load_dwordx4 v[52:55], v[60:61], off offset:2064
	s_nop 0
	global_load_dwordx4 v[60:63], v[60:61], off offset:2048
	s_brev_b32 s4, 64
	v_add_co_u32_e32 v112, vcc, s4, v74
	s_waitcnt vmcnt(7)
	v_cvt_pk_bf16_f32 v106, v32, v33
	v_cvt_pk_bf16_f32 v107, v34, v35
	s_waitcnt vmcnt(6)
	v_mov_b32_e32 v116, v41
	v_addc_co_u32_e32 v113, vcc, 0, v75, vcc
	v_mov_b32_e32 v117, v33
	v_cvt_pk_bf16_f32 v104, v40, v41
	v_cvt_pk_bf16_f32 v105, v42, v43
	v_mov_b32_e32 v114, v40
	v_mov_b32_e32 v115, v32
	s_waitcnt vmcnt(4)
	v_mov_b32_e32 v120, v45
	v_mov_b32_e32 v121, v37
	global_store_dwordx4 v[112:113], v[104:107], off nt
	v_pk_mul_f32 v[116:117], v[116:117], v[116:117]
	v_cvt_pk_bf16_f32 v108, v44, v45
	v_cvt_pk_bf16_f32 v109, v46, v47
	v_mov_b32_e32 v98, v42
	s_waitcnt vmcnt(3)
	v_mov_b32_e32 v106, v57
	v_mov_b32_e32 v107, v49
	v_mov_b32_e32 v99, v34
	v_mov_b32_e32 v118, v44
	v_mov_b32_e32 v119, v36
	v_mov_b32_e32 v104, v56
	v_mov_b32_e32 v105, v48
	v_pk_fma_f32 v[114:115], v[114:115], v[114:115], v[116:117]
	s_waitcnt vmcnt(1)
	v_mov_b32_e32 v116, v61
	v_mov_b32_e32 v117, v53
	v_pk_mul_f32 v[120:121], v[120:121], v[120:121]
	v_pk_mul_f32 v[106:107], v[106:107], v[106:107]
	v_cvt_pk_bf16_f32 v110, v36, v37
	v_cvt_pk_bf16_f32 v111, v38, v39
	v_mov_b32_e32 v96, v43
	v_mov_b32_e32 v97, v35
	v_mov_b32_e32 v102, v46
	v_mov_b32_e32 v103, v38
	global_store_dwordx4 v[112:113], v[108:111], off offset:1024 nt
	v_mov_b32_e32 v112, v60
	v_mov_b32_e32 v113, v52
	v_mov_b32_e32 v108, v58
	v_mov_b32_e32 v109, v50
	v_pk_fma_f32 v[118:119], v[118:119], v[118:119], v[120:121]
	v_pk_fma_f32 v[104:105], v[104:105], v[104:105], v[106:107]
	v_pk_mul_f32 v[116:117], v[116:117], v[116:117]
	v_pk_fma_f32 v[98:99], v[98:99], v[98:99], v[114:115]
	v_mov_b32_e32 v100, v47
	v_mov_b32_e32 v101, v39
	v_mov_b32_e32 v110, v59
	v_mov_b32_e32 v111, v51
	v_mov_b32_e32 v120, v62
	v_mov_b32_e32 v121, v54
	v_pk_fma_f32 v[112:113], v[112:113], v[112:113], v[116:117]
	v_pk_fma_f32 v[102:103], v[102:103], v[102:103], v[118:119]
	v_pk_fma_f32 v[104:105], v[108:109], v[108:109], v[104:105]
	v_pk_fma_f32 v[96:97], v[96:97], v[96:97], v[98:99]
	v_mov_b32_e32 v106, v63
	v_mov_b32_e32 v107, v55
	v_pk_fma_f32 v[108:109], v[120:121], v[120:121], v[112:113]
	v_pk_fma_f32 v[98:99], v[100:101], v[100:101], v[102:103]
	v_pk_fma_f32 v[100:101], v[110:111], v[110:111], v[104:105]
	v_add_f32_e32 v96, v96, v97
	v_pk_fma_f32 v[102:103], v[106:107], v[106:107], v[108:109]
	v_add_f32_e32 v97, v100, v101
	v_add_f32_e32 v96, v96, v98
	v_add_f32_e32 v97, v97, v102
	v_add_f32_e32 v96, v96, v99
	v_add_f32_e32 v97, v97, v103
	v_lshlrev_b64 v[122:123], 11, v[64:65]
	v_add_f32_dpp v96, v96, v96 quad_perm:[1,0,3,2] row_mask:0xf bank_mask:0xf bound_ctrl:1
	v_add_f32_dpp v97, v97, v97 quad_perm:[1,0,3,2] row_mask:0xf bank_mask:0xf bound_ctrl:1
	v_cvt_pk_bf16_f32 v64, v56, v57
	v_cvt_pk_bf16_f32 v65, v58, v59
	v_cvt_pk_bf16_f32 v66, v48, v49
	v_cvt_pk_bf16_f32 v67, v50, v51
	s_nop 0
	v_add_f32_dpp v96, v96, v96 quad_perm:[2,3,0,1] row_mask:0xf bank_mask:0xf bound_ctrl:1
	v_add_f32_dpp v97, v97, v97 quad_perm:[2,3,0,1] row_mask:0xf bank_mask:0xf bound_ctrl:1
	v_cvt_pk_bf16_f32 v68, v60, v61
	v_cvt_pk_bf16_f32 v69, v62, v63
	v_cvt_pk_bf16_f32 v70, v52, v53
	v_cvt_pk_bf16_f32 v71, v54, v55
	s_nop 0
	v_add_f32_dpp v96, v96, v96 row_half_mirror row_mask:0xf bank_mask:0xf bound_ctrl:1
	v_add_f32_dpp v97, v97, v97 row_half_mirror row_mask:0xf bank_mask:0xf bound_ctrl:1
	s_add_u32 s8, s8, 2
	v_add_f32_dpp v96, v96, v96 row_mirror row_mask:0xf bank_mask:0xf bound_ctrl:1
	v_add_f32_dpp v97, v97, v97 row_mirror row_mask:0xf bank_mask:0xf bound_ctrl:1
	v_readlane_b32 s11, v96, 16
	v_readlane_b32 s14, v96, 48
	v_readlane_b32 s4, v96, 0
	v_readlane_b32 s5, v96, 32
	v_readlane_b32 s12, v97, 0
	v_readlane_b32 s15, v97, 16
	v_readlane_b32 s13, v97, 32
	v_readlane_b32 s16, v97, 48
	v_mov_b32_e32 v96, s11
	v_mov_b32_e32 v97, s14
	v_pk_add_f32 v[96:97], s[4:5], v[96:97]
	v_mov_b32_e32 v98, s15
	v_mov_b32_e32 v99, s16
	v_add_f32_e32 v96, v96, v97
	v_pk_add_f32 v[98:99], s[12:13], v[98:99]
	v_fmamk_f32 v96, v96, 0x3a800000, v137
	v_add_f32_e32 v97, v98, v99
	v_mul_f32_e32 v98, 0x4b800000, v96
	v_cmp_gt_f32_e64 s[4:5], s18, v96
	v_fmamk_f32 v97, v97, 0x3a800000, v137
	v_mul_f32_e32 v99, 0x4b800000, v97
	v_cndmask_b32_e64 v96, v96, v98, s[4:5]
	v_cmp_gt_f32_e32 vcc, s18, v97
	v_rsq_f32_e32 v96, v96
	s_addc_u32 s9, s9, 0
	v_cndmask_b32_e32 v97, v97, v99, vcc
	v_rsq_f32_e32 v97, v97
	v_mul_f32_e32 v98, 0x45800000, v96
	v_cndmask_b32_e64 v96, v96, v98, s[4:5]
	v_lshl_add_u64 v[116:117], v[78:79], 0, v[122:123]
	v_mul_f32_e32 v99, 0x45800000, v97
	v_pk_mul_f32 v[34:35], v[34:35], v[96:97] op_sel_hi:[1,0]
	v_pk_mul_f32 v[32:33], v[32:33], v[96:97] op_sel_hi:[1,0]
	v_cndmask_b32_e32 v98, v97, v99, vcc
	v_pk_mul_f32 v[42:43], v[42:43], v[96:97] op_sel_hi:[1,0]
	v_pk_mul_f32 v[40:41], v[40:41], v[96:97] op_sel_hi:[1,0]
	v_pk_mul_f32 v[46:47], v[46:47], v[96:97] op_sel_hi:[1,0]
	v_pk_mul_f32 v[44:45], v[44:45], v[96:97] op_sel_hi:[1,0]
	v_pk_mul_f32 v[38:39], v[38:39], v[96:97] op_sel_hi:[1,0]
	v_pk_mul_f32 v[36:37], v[36:37], v[96:97] op_sel_hi:[1,0]
	v_pk_mul_f32 v[32:33], v[0:1], v[32:33]
	v_pk_mul_f32 v[34:35], v[2:3], v[34:35]
	v_pk_mul_f32 v[58:59], v[58:59], v[98:99] op_sel_hi:[1,0]
	v_pk_mul_f32 v[56:57], v[56:57], v[98:99] op_sel_hi:[1,0]
	v_pk_mul_f32 v[50:51], v[50:51], v[98:99] op_sel_hi:[1,0]
	v_pk_mul_f32 v[48:49], v[48:49], v[98:99] op_sel_hi:[1,0]
	v_pk_mul_f32 v[62:63], v[62:63], v[98:99] op_sel_hi:[1,0]
	v_pk_mul_f32 v[60:61], v[60:61], v[98:99] op_sel_hi:[1,0]
	v_pk_mul_f32 v[54:55], v[54:55], v[98:99] op_sel_hi:[1,0]
	v_pk_mul_f32 v[52:53], v[52:53], v[98:99] op_sel_hi:[1,0]
	v_pk_mul_f32 v[40:41], v[4:5], v[40:41]
	v_pk_mul_f32 v[42:43], v[6:7], v[42:43]
	v_pk_mul_f32 v[44:45], v[12:13], v[44:45]
	v_pk_mul_f32 v[46:47], v[14:15], v[46:47]
	v_pk_mul_f32 v[36:37], v[8:9], v[36:37]
	v_pk_mul_f32 v[38:39], v[10:11], v[38:39]
	v_pk_fma_f32 v[96:97], v[84:85], v[34:35], v[18:19]
	v_pk_fma_f32 v[34:35], v[86:87], v[32:33], v[16:17]
	v_pk_mul_f32 v[56:57], v[4:5], v[56:57]
	v_pk_mul_f32 v[58:59], v[6:7], v[58:59]
	v_pk_mul_f32 v[48:49], v[0:1], v[48:49]
	v_pk_mul_f32 v[50:51], v[2:3], v[50:51]
	v_pk_mul_f32 v[60:61], v[12:13], v[60:61]
	v_pk_mul_f32 v[62:63], v[14:15], v[62:63]
	v_pk_mul_f32 v[52:53], v[8:9], v[52:53]
	v_pk_mul_f32 v[54:55], v[10:11], v[54:55]
	v_pk_fma_f32 v[42:43], v[80:81], v[42:43], v[30:31]
	v_pk_fma_f32 v[40:41], v[82:83], v[40:41], v[28:29]
	v_pk_fma_f32 v[46:47], v[88:89], v[46:47], v[22:23]
	v_pk_fma_f32 v[44:45], v[90:91], v[44:45], v[20:21]
	v_pk_fma_f32 v[98:99], v[92:93], v[38:39], v[26:27]
	v_pk_fma_f32 v[38:39], v[94:95], v[36:37], v[24:25]
	v_cvt_pk_bf16_f32 v32, v40, v41
	v_cvt_pk_bf16_f32 v33, v42, v43
	v_cvt_pk_bf16_f32 v34, v34, v35
	v_cvt_pk_bf16_f32 v35, v96, v97
	v_lshl_add_u64 v[122:123], v[76:77], 0, v[122:123]
	s_cmp_lt_i32 s8, s10
	v_pk_fma_f32 v[58:59], v[80:81], v[58:59], v[30:31]
	v_pk_fma_f32 v[56:57], v[82:83], v[56:57], v[28:29]
	v_pk_fma_f32 v[50:51], v[84:85], v[50:51], v[18:19]
	v_pk_fma_f32 v[48:49], v[86:87], v[48:49], v[16:17]
	v_pk_fma_f32 v[62:63], v[88:89], v[62:63], v[22:23]
	v_pk_fma_f32 v[60:61], v[90:91], v[60:61], v[20:21]
	v_pk_fma_f32 v[54:55], v[92:93], v[54:55], v[26:27]
	v_pk_fma_f32 v[52:53], v[94:95], v[52:53], v[24:25]
	v_cvt_pk_bf16_f32 v36, v44, v45
	v_cvt_pk_bf16_f32 v37, v46, v47
	v_cvt_pk_bf16_f32 v38, v38, v39
	v_cvt_pk_bf16_f32 v39, v98, v99
	v_cvt_pk_bf16_f32 v40, v56, v57
	v_cvt_pk_bf16_f32 v41, v58, v59
	v_cvt_pk_bf16_f32 v42, v48, v49
	v_cvt_pk_bf16_f32 v43, v50, v51
	v_cvt_pk_bf16_f32 v44, v60, v61
	v_cvt_pk_bf16_f32 v45, v62, v63
	s_nop 0
	v_cvt_pk_bf16_f32 v46, v52, v53
	v_cvt_pk_bf16_f32 v47, v54, v55
	global_store_dwordx4 v[74:75], v[32:35], off nt
	global_store_dwordx4 v[74:75], v[36:39], off offset:1024 nt
	global_store_dwordx4 v[116:117], v[64:67], off nt
	global_store_dwordx4 v[116:117], v[68:71], off offset:1024 nt
	global_store_dwordx4 v[122:123], v[40:43], off nt
	global_store_dwordx4 v[122:123], v[44:47], off offset:1024 nt
	v_lshl_add_u64 v[74:75], v[74:75], 0, s[30:31]
	s_cbranch_scc1 .LBB0_1254
